# v31 + conv pre-stage fifth tile round (layer 0) spread over all 8 XCDs (8 WGs each) instead of 2 XCDs
# speedup vs baseline: 1.0046x; 1.0046x over previous
.LBB0_356:
	s_or_b64 exec, exec, s[68:69]
	s_and_b64 s[0:1], s[90:91], exec
	s_movk_i32 s0, 0x440
	s_cselect_b32 s5, 0x400, s0
	v_readlane_b32 s0, v253, 0
	v_readlane_b32 s20, v253, 30
	v_readlane_b32 s21, v253, 31
	v_readlane_b32 s22, v253, 32
	v_readlane_b32 s23, v253, 33
	s_and_b32 s1, s0, 7
	s_lshl_b32 s1, s1, 5
	s_lshr_b32 s0, s0, 3
	s_add_u32 s4, s1, s0
	s_lshr_b32 s26, s1, 5
	s_lshl_b32 s27, s0, 3
	s_add_u32 s26, s26, s27
	s_add_u32 s26, s26, 0x400
	v_and_b32_e32 v242, 31, v143
	v_lshrrev_b32_e32 v241, 5, v143
	v_mul_u32_u24_e32 v228, 0x1440, v241
	v_lshl_add_u32 v228, v242, 4, v228
	v_add_u32_e32 v228, 0x840, v228
	v_add_u32_e32 v229, 0x14400, v228
	v_add_u32_e32 v230, 0x28800, v228
	v_add_u32_e32 v231, 0x3cc00, v228
	v_lshlrev_b32_e32 v232, 10, v241
	v_lshl_add_u32 v232, v242, 5, v232
	v_and_b32_e32 v243, 0xff, v143
	v_lshrrev_b32_e32 v244, 8, v143
	v_lshlrev_b32_e32 v237, 14, v244
	v_lshl_add_u32 v237, v243, 2, v237
	v_add_u32_e32 v238, 0x10000, v237
	v_and_b32_e32 v245, 63, v143
	v_lshrrev_b32_e32 v246, 6, v143
	v_lshlrev_b32_e32 v239, 12, v246
	v_lshl_add_u32 v239, v245, 4, v239
	v_add_u32_e32 v239, 0x10000, v239
	v_lshlrev_b32_e32 v240, 11, v246
	v_lshl_add_u32 v240, v245, 3, v240
	v_lshlrev_b32_e32 v247, 2, v243
	v_lshlrev_b32_e32 v248, 4, v245
	s_sub_u32 s16, s4, 0x400
	s_lshr_b32 s17, s16, 3
	s_lshl_b32 s17, s17, 8
	s_add_u32 s17, s17, 0x8000
	s_and_b32 s16, s16, 7
	s_lshr_b32 s14, s4, 7
	s_lshl_b32 s14, s14, 12
	s_and_b32 s15, s4, 0x7f
	s_cmp_lt_u32 s4, 0x400
	s_cselect_b32 s14, s14, s17
	s_cselect_b32 s15, s15, s16
	s_movk_i32 s16, 0x100
	s_cselect_b32 s10, 0x1000, s16
	s_lshl_b32 s15, s15, 5
	s_add_u32 s14, s14, s15
	s_sub_u32 s16, s14, 15
	s_mul_i32 s16, s16, 0x1440
	s_ashr_i32 s17, s16, 31
	s_add_u32 s6, s50, s16
	s_addc_u32 s7, s51, s17
	s_add_u32 s6, s6, 0x5cbd000
	s_addc_u32 s7, s7, 0
	global_load_dwordx4 v[188:191], v228, s[6:7]
	global_load_dwordx4 v[192:195], v228, s[6:7] offset:512
	global_load_dwordx4 v[196:199], v229, s[6:7]
	global_load_dwordx4 v[200:203], v229, s[6:7] offset:512
	global_load_dwordx4 v[204:207], v230, s[6:7]
	global_load_dwordx4 v[208:211], v230, s[6:7] offset:512
	global_load_dwordx4 v[212:215], v231, s[6:7]
	global_load_dwordx4 v[216:219], v231, s[6:7] offset:512
	s_mul_i32 s0, s74, 0x7c00
	s_add_u32 s20, s20, s0
	s_addc_u32 s21, s21, 0
	global_load_dword v96, v247, s[20:21] offset:0
	global_load_dword v97, v247, s[20:21] offset:1024
	global_load_dword v98, v247, s[20:21] offset:2048
	global_load_dword v99, v247, s[20:21] offset:3072
	s_add_u32 s20, s20, 0x1000
	s_addc_u32 s21, s21, 0
	global_load_dword v100, v247, s[20:21] offset:0
	global_load_dword v101, v247, s[20:21] offset:1024
	global_load_dword v102, v247, s[20:21] offset:2048
	global_load_dword v103, v247, s[20:21] offset:3072
	s_add_u32 s20, s20, 0x1000
	s_addc_u32 s21, s21, 0
	global_load_dword v104, v247, s[20:21] offset:0
	global_load_dword v105, v247, s[20:21] offset:1024
	global_load_dword v106, v247, s[20:21] offset:2048
	global_load_dword v107, v247, s[20:21] offset:3072
	s_add_u32 s20, s20, 0x1000
	s_addc_u32 s21, s21, 0
	global_load_dword v108, v247, s[20:21] offset:0
	global_load_dword v109, v247, s[20:21] offset:1024
	global_load_dword v110, v247, s[20:21] offset:2048
	global_load_dword v111, v247, s[20:21] offset:3072
	s_add_u32 s20, s20, 0x1000
	s_addc_u32 s21, s21, 0
	global_load_dword v112, v247, s[20:21] offset:0
	global_load_dword v113, v247, s[20:21] offset:1024
	global_load_dword v114, v247, s[20:21] offset:2048
	global_load_dword v115, v247, s[20:21] offset:3072
	s_add_u32 s20, s20, 0x1000
	s_addc_u32 s21, s21, 0
	global_load_dword v116, v247, s[20:21] offset:0
	global_load_dword v117, v247, s[20:21] offset:1024
	global_load_dword v118, v247, s[20:21] offset:2048
	global_load_dword v119, v247, s[20:21] offset:3072
	s_add_u32 s20, s20, 0x1000
	s_addc_u32 s21, s21, 0
	global_load_dword v120, v247, s[20:21] offset:0
	global_load_dword v121, v247, s[20:21] offset:1024
	global_load_dword v122, v247, s[20:21] offset:2048
	global_load_dword v123, v247, s[20:21] offset:3072
	s_add_u32 s20, s20, 0x1000
	s_addc_u32 s21, s21, 0
	global_load_dword v124, v247, s[20:21] offset:0
	global_load_dword v125, v247, s[20:21] offset:1024
	global_load_dword v126, v247, s[20:21] offset:2048
	s_lshl_b32 s0, s74, 10
	s_add_u32 s22, s22, s0
	s_addc_u32 s23, s23, 0
	global_load_dword v127, v247, s[22:23]
	s_add_u32 s16, s36, s0
	s_addc_u32 s17, s37, 0
	global_load_dwordx4 v[220:223], v248, s[16:17]
	s_add_u32 s18, s38, s0
	s_addc_u32 s19, s39, 0
	global_load_dwordx4 v[224:227], v248, s[18:19]
	s_waitcnt vmcnt(0)

.Lcv_nm3:
	v_lshlrev_b32_e32 v16, 16, v216
	v_and_b32_e32 v17, 0xffff0000, v216
	v_lshlrev_b32_e32 v18, 16, v217
	v_and_b32_e32 v19, 0xffff0000, v217
	v_lshlrev_b32_e32 v20, 16, v218
	v_and_b32_e32 v21, 0xffff0000, v218
	v_lshlrev_b32_e32 v22, 16, v219
	v_and_b32_e32 v23, 0xffff0000, v219
	v_mul_f32_e32 v16, 0xbfb8aa3b, v16
	v_mul_f32_e32 v17, 0xbfb8aa3b, v17
	v_mul_f32_e32 v18, 0xbfb8aa3b, v18
	v_mul_f32_e32 v19, 0xbfb8aa3b, v19
	v_mul_f32_e32 v20, 0xbfb8aa3b, v20
	v_mul_f32_e32 v21, 0xbfb8aa3b, v21
	v_mul_f32_e32 v22, 0xbfb8aa3b, v22
	v_mul_f32_e32 v23, 0xbfb8aa3b, v23
	v_exp_f32_e32 v16, v16
	v_exp_f32_e32 v17, v17
	v_exp_f32_e32 v18, v18
	v_exp_f32_e32 v19, v19
	v_exp_f32_e32 v20, v20
	v_exp_f32_e32 v21, v21
	v_exp_f32_e32 v22, v22
	v_exp_f32_e32 v23, v23
	v_add_f32_e32 v16, 1.0, v16
	v_add_f32_e32 v17, 1.0, v17
	v_add_f32_e32 v18, 1.0, v18
	v_add_f32_e32 v19, 1.0, v19
	v_add_f32_e32 v20, 1.0, v20
	v_add_f32_e32 v21, 1.0, v21
	v_add_f32_e32 v22, 1.0, v22
	v_add_f32_e32 v23, 1.0, v23
	v_rcp_f32_e32 v16, v16
	v_rcp_f32_e32 v17, v17
	v_rcp_f32_e32 v18, v18
	v_rcp_f32_e32 v19, v19
	v_rcp_f32_e32 v20, v20
	v_rcp_f32_e32 v21, v21
	v_rcp_f32_e32 v22, v22
	v_rcp_f32_e32 v23, v23
	v_lshlrev_b32_e32 v24, 16, v212
	v_and_b32_e32 v25, 0xffff0000, v212
	v_lshlrev_b32_e32 v26, 16, v213
	v_and_b32_e32 v27, 0xffff0000, v213
	v_lshlrev_b32_e32 v28, 16, v214
	v_and_b32_e32 v29, 0xffff0000, v214
	v_lshlrev_b32_e32 v30, 16, v215
	v_and_b32_e32 v31, 0xffff0000, v215
	v_mul_f32_e32 v24, v24, v16
	v_mul_f32_e32 v25, v25, v17
	v_mul_f32_e32 v26, v26, v18
	v_mul_f32_e32 v27, v27, v19
	v_mul_f32_e32 v28, v28, v20
	v_mul_f32_e32 v29, v29, v21
	v_mul_f32_e32 v30, v30, v22
	v_mul_f32_e32 v31, v31, v23
	ds_write_b128 v232, v[24:27] offset:49152
	ds_write_b128 v232, v[28:31] offset:49168
	s_waitcnt lgkmcnt(0)
	s_barrier
	s_add_u32 s13, s4, 0x100
	s_cmp_ge_u32 s13, 0x400
	s_cselect_b32 s13, s26, s13
	s_cmp_ge_u32 s4, 0x400
	s_cselect_b32 s13, 0x7fff, s13
	s_cmp_lt_u32 s13, s5
	s_cselect_b32 s18, s13, s4
	s_sub_u32 s16, s18, 0x400
	s_lshr_b32 s17, s16, 3
	s_lshl_b32 s17, s17, 8
	s_add_u32 s17, s17, 0x8000
	s_and_b32 s16, s16, 7
	s_lshr_b32 s14, s18, 7
	s_lshl_b32 s14, s14, 12
	s_and_b32 s15, s18, 0x7f
	s_cmp_lt_u32 s18, 0x400
	s_cselect_b32 s14, s14, s17
	s_cselect_b32 s15, s15, s16
	s_movk_i32 s16, 0x100
	s_cselect_b32 s19, 0x1000, s16
	s_lshl_b32 s15, s15, 5
	s_add_u32 s14, s14, s15
	s_sub_u32 s16, s14, 15
	s_mul_i32 s16, s16, 0x1440
	s_ashr_i32 s17, s16, 31
	s_add_u32 s6, s50, s16
	s_addc_u32 s7, s51, s17
	s_add_u32 s6, s6, 0x5cbd000
	s_addc_u32 s7, s7, 0
	global_load_dwordx4 v[188:191], v228, s[6:7]
	global_load_dwordx4 v[192:195], v228, s[6:7] offset:512
	global_load_dwordx4 v[196:199], v229, s[6:7]
	global_load_dwordx4 v[200:203], v229, s[6:7] offset:512
	global_load_dwordx4 v[204:207], v230, s[6:7]
	global_load_dwordx4 v[208:211], v230, s[6:7] offset:512
	global_load_dwordx4 v[212:215], v231, s[6:7]
	global_load_dwordx4 v[216:219], v231, s[6:7] offset:512
	ds_read2st64_b32 v[48:49], v237 offset0:0 offset1:4
	ds_read2st64_b32 v[50:51], v237 offset0:8 offset1:12
	ds_read2st64_b32 v[52:53], v237 offset0:16 offset1:20
	ds_read2st64_b32 v[54:55], v237 offset0:24 offset1:28
	ds_read2st64_b32 v[56:57], v237 offset0:32 offset1:36
	ds_read2st64_b32 v[58:59], v237 offset0:40 offset1:44
	ds_read2st64_b32 v[60:61], v237 offset0:48 offset1:52
	ds_read2st64_b32 v[62:63], v237 offset0:56 offset1:60
	ds_read2st64_b32 v[64:65], v237 offset0:64 offset1:68
	ds_read2st64_b32 v[66:67], v237 offset0:72 offset1:76
	ds_read2st64_b32 v[68:69], v237 offset0:80 offset1:84
	ds_read2st64_b32 v[70:71], v237 offset0:88 offset1:92
	s_waitcnt lgkmcnt(11)
	v_fma_f32 v0, v96, v48, v127
	v_fmac_f32_e32 v0, v97, v49
	v_fma_f32 v1, v96, v49, v127
	ds_read2st64_b32 v[48:49], v237 offset0:96 offset1:100
	s_waitcnt lgkmcnt(11)
	v_fmac_f32_e32 v0, v98, v50
	v_fmac_f32_e32 v1, v97, v50
	v_fma_f32 v2, v96, v50, v127
	v_fmac_f32_e32 v0, v99, v51
	v_fmac_f32_e32 v1, v98, v51
	v_fmac_f32_e32 v2, v97, v51
	v_fma_f32 v3, v96, v51, v127
	ds_read2st64_b32 v[50:51], v237 offset0:104 offset1:108
	s_waitcnt lgkmcnt(11)
	v_fmac_f32_e32 v0, v100, v52
	v_fmac_f32_e32 v1, v99, v52
	v_fmac_f32_e32 v2, v98, v52
	v_fmac_f32_e32 v3, v97, v52
	v_fma_f32 v4, v96, v52, v127
	v_fmac_f32_e32 v0, v101, v53
	v_fmac_f32_e32 v1, v100, v53
	v_fmac_f32_e32 v2, v99, v53
	v_fmac_f32_e32 v3, v98, v53
	v_fmac_f32_e32 v4, v97, v53
	v_fma_f32 v5, v96, v53, v127
	ds_read2st64_b32 v[52:53], v237 offset0:112 offset1:116
	s_waitcnt lgkmcnt(11)
	v_fmac_f32_e32 v0, v102, v54
	v_fmac_f32_e32 v1, v101, v54
	v_fmac_f32_e32 v2, v100, v54
	v_fmac_f32_e32 v3, v99, v54
	v_fmac_f32_e32 v4, v98, v54
	v_fmac_f32_e32 v5, v97, v54
	v_fma_f32 v6, v96, v54, v127
	v_fmac_f32_e32 v0, v103, v55
	v_fmac_f32_e32 v1, v102, v55
	v_fmac_f32_e32 v2, v101, v55
	v_fmac_f32_e32 v3, v100, v55
	v_fmac_f32_e32 v4, v99, v55
	v_fmac_f32_e32 v5, v98, v55
	v_fmac_f32_e32 v6, v97, v55
	v_fma_f32 v7, v96, v55, v127
	ds_read2st64_b32 v[54:55], v237 offset0:120 offset1:124
	s_waitcnt lgkmcnt(11)
	v_fmac_f32_e32 v0, v104, v56
	v_fmac_f32_e32 v1, v103, v56
	v_fmac_f32_e32 v2, v102, v56
	v_fmac_f32_e32 v3, v101, v56
	v_fmac_f32_e32 v4, v100, v56
	v_fmac_f32_e32 v5, v99, v56
	v_fmac_f32_e32 v6, v98, v56
	v_fmac_f32_e32 v7, v97, v56
	v_fma_f32 v8, v96, v56, v127
	v_fmac_f32_e32 v0, v105, v57
	v_fmac_f32_e32 v1, v104, v57
	v_fmac_f32_e32 v2, v103, v57
	v_fmac_f32_e32 v3, v102, v57
	v_fmac_f32_e32 v4, v101, v57
	v_fmac_f32_e32 v5, v100, v57
	v_fmac_f32_e32 v6, v99, v57
	v_fmac_f32_e32 v7, v98, v57
	v_fmac_f32_e32 v8, v97, v57
	v_fma_f32 v9, v96, v57, v127
	ds_read2st64_b32 v[56:57], v237 offset0:128 offset1:132
	s_waitcnt lgkmcnt(11)
	v_fmac_f32_e32 v0, v106, v58
	v_fmac_f32_e32 v1, v105, v58
	v_fmac_f32_e32 v2, v104, v58
	v_fmac_f32_e32 v3, v103, v58
	v_fmac_f32_e32 v4, v102, v58
	v_fmac_f32_e32 v5, v101, v58
	v_fmac_f32_e32 v6, v100, v58
	v_fmac_f32_e32 v7, v99, v58
	v_fmac_f32_e32 v8, v98, v58
	v_fmac_f32_e32 v9, v97, v58
	v_fma_f32 v10, v96, v58, v127
	v_fmac_f32_e32 v0, v107, v59
	v_fmac_f32_e32 v1, v106, v59
	v_fmac_f32_e32 v2, v105, v59
	v_fmac_f32_e32 v3, v104, v59
	v_fmac_f32_e32 v4, v103, v59
	v_fmac_f32_e32 v5, v102, v59
	v_fmac_f32_e32 v6, v101, v59
	v_fmac_f32_e32 v7, v100, v59
	v_fmac_f32_e32 v8, v99, v59
	v_fmac_f32_e32 v9, v98, v59
	v_fmac_f32_e32 v10, v97, v59
	v_fma_f32 v11, v96, v59, v127
	ds_read2st64_b32 v[58:59], v237 offset0:136 offset1:140
	s_waitcnt lgkmcnt(11)
	v_fmac_f32_e32 v0, v108, v60
	v_fmac_f32_e32 v1, v107, v60
	v_fmac_f32_e32 v2, v106, v60
	v_fmac_f32_e32 v3, v105, v60
	v_fmac_f32_e32 v4, v104, v60
	v_fmac_f32_e32 v5, v103, v60
	v_fmac_f32_e32 v6, v102, v60
	v_fmac_f32_e32 v7, v101, v60
	v_fmac_f32_e32 v8, v100, v60
	v_fmac_f32_e32 v9, v99, v60
	v_fmac_f32_e32 v10, v98, v60
	v_fmac_f32_e32 v11, v97, v60
	v_fma_f32 v12, v96, v60, v127
	v_fmac_f32_e32 v0, v109, v61
	v_fmac_f32_e32 v1, v108, v61
	v_fmac_f32_e32 v2, v107, v61
	v_fmac_f32_e32 v3, v106, v61
	v_fmac_f32_e32 v4, v105, v61
	v_fmac_f32_e32 v5, v104, v61
	v_fmac_f32_e32 v6, v103, v61
	v_fmac_f32_e32 v7, v102, v61
	v_fmac_f32_e32 v8, v101, v61
	v_fmac_f32_e32 v9, v100, v61
	v_fmac_f32_e32 v10, v99, v61
	v_fmac_f32_e32 v11, v98, v61
	v_fmac_f32_e32 v12, v97, v61
	v_fma_f32 v13, v96, v61, v127
	ds_read2st64_b32 v[60:61], v237 offset0:144 offset1:148
	s_waitcnt lgkmcnt(11)
	v_fmac_f32_e32 v0, v110, v62
	v_fmac_f32_e32 v1, v109, v62
	v_fmac_f32_e32 v2, v108, v62
	v_fmac_f32_e32 v3, v107, v62
	v_fmac_f32_e32 v4, v106, v62
	v_fmac_f32_e32 v5, v105, v62
	v_fmac_f32_e32 v6, v104, v62
	v_fmac_f32_e32 v7, v103, v62
	v_fmac_f32_e32 v8, v102, v62
	v_fmac_f32_e32 v9, v101, v62
	v_fmac_f32_e32 v10, v100, v62
	v_fmac_f32_e32 v11, v99, v62
	v_fmac_f32_e32 v12, v98, v62
	v_fmac_f32_e32 v13, v97, v62
	v_fma_f32 v14, v96, v62, v127
	v_fmac_f32_e32 v0, v111, v63
	v_fmac_f32_e32 v1, v110, v63
	v_fmac_f32_e32 v2, v109, v63
	v_fmac_f32_e32 v3, v108, v63
	v_fmac_f32_e32 v4, v107, v63
	v_fmac_f32_e32 v5, v106, v63
	v_fmac_f32_e32 v6, v105, v63
	v_fmac_f32_e32 v7, v104, v63
	v_fmac_f32_e32 v8, v103, v63
	v_fmac_f32_e32 v9, v102, v63
	v_fmac_f32_e32 v10, v101, v63
	v_fmac_f32_e32 v11, v100, v63
	v_fmac_f32_e32 v12, v99, v63
	v_fmac_f32_e32 v13, v98, v63
	v_fmac_f32_e32 v14, v97, v63
	v_fma_f32 v15, v96, v63, v127
	ds_read2st64_b32 v[62:63], v237 offset0:152 offset1:156
	s_waitcnt lgkmcnt(11)
	v_fmac_f32_e32 v0, v112, v64
	v_fmac_f32_e32 v1, v111, v64
	v_fmac_f32_e32 v2, v110, v64
	v_fmac_f32_e32 v3, v109, v64
	v_fmac_f32_e32 v4, v108, v64
	v_fmac_f32_e32 v5, v107, v64
	v_fmac_f32_e32 v6, v106, v64
	v_fmac_f32_e32 v7, v105, v64
	v_fmac_f32_e32 v8, v104, v64
	v_fmac_f32_e32 v9, v103, v64
	v_fmac_f32_e32 v10, v102, v64
	v_fmac_f32_e32 v11, v101, v64
	v_fmac_f32_e32 v12, v100, v64
	v_fmac_f32_e32 v13, v99, v64
	v_fmac_f32_e32 v14, v98, v64
	v_fmac_f32_e32 v15, v97, v64
	v_fmac_f32_e32 v0, v113, v65
	v_fmac_f32_e32 v1, v112, v65
	v_fmac_f32_e32 v2, v111, v65
	v_fmac_f32_e32 v3, v110, v65
	v_fmac_f32_e32 v4, v109, v65
	v_fmac_f32_e32 v5, v108, v65
	v_fmac_f32_e32 v6, v107, v65
	v_fmac_f32_e32 v7, v106, v65
	v_fmac_f32_e32 v8, v105, v65
	v_fmac_f32_e32 v9, v104, v65
	v_fmac_f32_e32 v10, v103, v65
	v_fmac_f32_e32 v11, v102, v65
	v_fmac_f32_e32 v12, v101, v65
	v_fmac_f32_e32 v13, v100, v65
	v_fmac_f32_e32 v14, v99, v65
	v_fmac_f32_e32 v15, v98, v65
	ds_read2st64_b32 v[64:65], v237 offset0:160 offset1:164
	s_waitcnt lgkmcnt(11)
	v_fmac_f32_e32 v0, v114, v66
	v_fmac_f32_e32 v1, v113, v66
	v_fmac_f32_e32 v2, v112, v66
	v_fmac_f32_e32 v3, v111, v66
	v_fmac_f32_e32 v4, v110, v66
	v_fmac_f32_e32 v5, v109, v66
	v_fmac_f32_e32 v6, v108, v66
	v_fmac_f32_e32 v7, v107, v66
	v_fmac_f32_e32 v8, v106, v66
	v_fmac_f32_e32 v9, v105, v66
	v_fmac_f32_e32 v10, v104, v66
	v_fmac_f32_e32 v11, v103, v66
	v_fmac_f32_e32 v12, v102, v66
	v_fmac_f32_e32 v13, v101, v66
	v_fmac_f32_e32 v14, v100, v66
	v_fmac_f32_e32 v15, v99, v66
	v_fmac_f32_e32 v0, v115, v67
	v_fmac_f32_e32 v1, v114, v67
	v_fmac_f32_e32 v2, v113, v67
	v_fmac_f32_e32 v3, v112, v67
	v_fmac_f32_e32 v4, v111, v67
	v_fmac_f32_e32 v5, v110, v67
	v_fmac_f32_e32 v6, v109, v67
	v_fmac_f32_e32 v7, v108, v67
	v_fmac_f32_e32 v8, v107, v67
	v_fmac_f32_e32 v9, v106, v67
	v_fmac_f32_e32 v10, v105, v67
	v_fmac_f32_e32 v11, v104, v67
	v_fmac_f32_e32 v12, v103, v67
	v_fmac_f32_e32 v13, v102, v67
	v_fmac_f32_e32 v14, v101, v67
	v_fmac_f32_e32 v15, v100, v67
	ds_read2st64_b32 v[66:67], v237 offset0:168 offset1:172
	s_waitcnt lgkmcnt(11)
	v_fmac_f32_e32 v0, v116, v68
	v_fmac_f32_e32 v1, v115, v68
	v_fmac_f32_e32 v2, v114, v68
	v_fmac_f32_e32 v3, v113, v68
	v_fmac_f32_e32 v4, v112, v68
	v_fmac_f32_e32 v5, v111, v68
	v_fmac_f32_e32 v6, v110, v68
	v_fmac_f32_e32 v7, v109, v68
	v_fmac_f32_e32 v8, v108, v68
	v_fmac_f32_e32 v9, v107, v68
	v_fmac_f32_e32 v10, v106, v68
	v_fmac_f32_e32 v11, v105, v68
	v_fmac_f32_e32 v12, v104, v68
	v_fmac_f32_e32 v13, v103, v68
	v_fmac_f32_e32 v14, v102, v68
	v_fmac_f32_e32 v15, v101, v68
	v_fmac_f32_e32 v0, v117, v69
	v_fmac_f32_e32 v1, v116, v69
	v_fmac_f32_e32 v2, v115, v69
	v_fmac_f32_e32 v3, v114, v69
	v_fmac_f32_e32 v4, v113, v69
	v_fmac_f32_e32 v5, v112, v69
	v_fmac_f32_e32 v6, v111, v69
	v_fmac_f32_e32 v7, v110, v69
	v_fmac_f32_e32 v8, v109, v69
	v_fmac_f32_e32 v9, v108, v69
	v_fmac_f32_e32 v10, v107, v69
	v_fmac_f32_e32 v11, v106, v69
	v_fmac_f32_e32 v12, v105, v69
	v_fmac_f32_e32 v13, v104, v69
	v_fmac_f32_e32 v14, v103, v69
	v_fmac_f32_e32 v15, v102, v69
	ds_read2st64_b32 v[68:69], v237 offset0:176 offset1:180
	s_waitcnt lgkmcnt(11)
	v_fmac_f32_e32 v0, v118, v70
	v_fmac_f32_e32 v1, v117, v70
	v_fmac_f32_e32 v2, v116, v70
	v_fmac_f32_e32 v3, v115, v70
	v_fmac_f32_e32 v4, v114, v70
	v_fmac_f32_e32 v5, v113, v70
	v_fmac_f32_e32 v6, v112, v70
	v_fmac_f32_e32 v7, v111, v70
	v_fmac_f32_e32 v8, v110, v70
	v_fmac_f32_e32 v9, v109, v70
	v_fmac_f32_e32 v10, v108, v70
	v_fmac_f32_e32 v11, v107, v70
	v_fmac_f32_e32 v12, v106, v70
	v_fmac_f32_e32 v13, v105, v70
	v_fmac_f32_e32 v14, v104, v70
	v_fmac_f32_e32 v15, v103, v70
	v_fmac_f32_e32 v0, v119, v71
	v_fmac_f32_e32 v1, v118, v71
	v_fmac_f32_e32 v2, v117, v71
	v_fmac_f32_e32 v3, v116, v71
	v_fmac_f32_e32 v4, v115, v71
	v_fmac_f32_e32 v5, v114, v71
	v_fmac_f32_e32 v6, v113, v71
	v_fmac_f32_e32 v7, v112, v71
	v_fmac_f32_e32 v8, v111, v71
	v_fmac_f32_e32 v9, v110, v71
	v_fmac_f32_e32 v10, v109, v71
	v_fmac_f32_e32 v11, v108, v71
	v_fmac_f32_e32 v12, v107, v71
	v_fmac_f32_e32 v13, v106, v71
	v_fmac_f32_e32 v14, v105, v71
	v_fmac_f32_e32 v15, v104, v71
	s_waitcnt lgkmcnt(10)
	v_fmac_f32_e32 v0, v120, v48
	v_fmac_f32_e32 v1, v119, v48
	v_fmac_f32_e32 v2, v118, v48
	v_fmac_f32_e32 v3, v117, v48
	v_fmac_f32_e32 v4, v116, v48
	v_fmac_f32_e32 v5, v115, v48
	v_fmac_f32_e32 v6, v114, v48
	v_fmac_f32_e32 v7, v113, v48
	v_fmac_f32_e32 v8, v112, v48
	v_fmac_f32_e32 v9, v111, v48
	v_fmac_f32_e32 v10, v110, v48
	v_fmac_f32_e32 v11, v109, v48
	v_fmac_f32_e32 v12, v108, v48
	v_fmac_f32_e32 v13, v107, v48
	v_fmac_f32_e32 v14, v106, v48
	v_fmac_f32_e32 v15, v105, v48
	v_fmac_f32_e32 v0, v121, v49
	v_fmac_f32_e32 v1, v120, v49
	v_fmac_f32_e32 v2, v119, v49
	v_fmac_f32_e32 v3, v118, v49
	v_fmac_f32_e32 v4, v117, v49
	v_fmac_f32_e32 v5, v116, v49
	v_fmac_f32_e32 v6, v115, v49
	v_fmac_f32_e32 v7, v114, v49
	v_fmac_f32_e32 v8, v113, v49
	v_fmac_f32_e32 v9, v112, v49
	v_fmac_f32_e32 v10, v111, v49
	v_fmac_f32_e32 v11, v110, v49
	v_fmac_f32_e32 v12, v109, v49
	v_fmac_f32_e32 v13, v108, v49
	v_fmac_f32_e32 v14, v107, v49
	v_fmac_f32_e32 v15, v106, v49
	s_waitcnt lgkmcnt(9)
	v_fmac_f32_e32 v0, v122, v50
	v_fmac_f32_e32 v1, v121, v50
	v_fmac_f32_e32 v2, v120, v50
	v_fmac_f32_e32 v3, v119, v50
	v_fmac_f32_e32 v4, v118, v50
	v_fmac_f32_e32 v5, v117, v50
	v_fmac_f32_e32 v6, v116, v50
	v_fmac_f32_e32 v7, v115, v50
	v_fmac_f32_e32 v8, v114, v50
	v_fmac_f32_e32 v9, v113, v50
	v_fmac_f32_e32 v10, v112, v50
	v_fmac_f32_e32 v11, v111, v50
	v_fmac_f32_e32 v12, v110, v50
	v_fmac_f32_e32 v13, v109, v50
	v_fmac_f32_e32 v14, v108, v50
	v_fmac_f32_e32 v15, v107, v50
	v_fmac_f32_e32 v0, v123, v51
	v_fmac_f32_e32 v1, v122, v51
	v_fmac_f32_e32 v2, v121, v51
	v_fmac_f32_e32 v3, v120, v51
	v_fmac_f32_e32 v4, v119, v51
	v_fmac_f32_e32 v5, v118, v51
	v_fmac_f32_e32 v6, v117, v51
	v_fmac_f32_e32 v7, v116, v51
	v_fmac_f32_e32 v8, v115, v51
	v_fmac_f32_e32 v9, v114, v51
	v_fmac_f32_e32 v10, v113, v51
	v_fmac_f32_e32 v11, v112, v51
	v_fmac_f32_e32 v12, v111, v51
	v_fmac_f32_e32 v13, v110, v51
	v_fmac_f32_e32 v14, v109, v51
	v_fmac_f32_e32 v15, v108, v51
	s_waitcnt lgkmcnt(8)
	v_fmac_f32_e32 v0, v124, v52
	v_fmac_f32_e32 v1, v123, v52
	v_fmac_f32_e32 v2, v122, v52
	v_fmac_f32_e32 v3, v121, v52
	v_fmac_f32_e32 v4, v120, v52
	v_fmac_f32_e32 v5, v119, v52
	v_fmac_f32_e32 v6, v118, v52
	v_fmac_f32_e32 v7, v117, v52
	v_fmac_f32_e32 v8, v116, v52
	v_fmac_f32_e32 v9, v115, v52
	v_fmac_f32_e32 v10, v114, v52
	v_fmac_f32_e32 v11, v113, v52
	v_fmac_f32_e32 v12, v112, v52
	v_fmac_f32_e32 v13, v111, v52
	v_fmac_f32_e32 v14, v110, v52
	v_fmac_f32_e32 v15, v109, v52
	v_fmac_f32_e32 v0, v125, v53
	v_fmac_f32_e32 v1, v124, v53
	v_fmac_f32_e32 v2, v123, v53
	v_fmac_f32_e32 v3, v122, v53
	v_fmac_f32_e32 v4, v121, v53
	v_fmac_f32_e32 v5, v120, v53
	v_fmac_f32_e32 v6, v119, v53
	v_fmac_f32_e32 v7, v118, v53
	v_fmac_f32_e32 v8, v117, v53
	v_fmac_f32_e32 v9, v116, v53
	v_fmac_f32_e32 v10, v115, v53
	v_fmac_f32_e32 v11, v114, v53
	v_fmac_f32_e32 v12, v113, v53
	v_fmac_f32_e32 v13, v112, v53
	v_fmac_f32_e32 v14, v111, v53
	v_fmac_f32_e32 v15, v110, v53
	s_waitcnt lgkmcnt(7)
	v_fmac_f32_e32 v0, v126, v54
	v_fmac_f32_e32 v1, v125, v54
	v_fmac_f32_e32 v2, v124, v54
	v_fmac_f32_e32 v3, v123, v54
	v_fmac_f32_e32 v4, v122, v54
	v_fmac_f32_e32 v5, v121, v54
	v_fmac_f32_e32 v6, v120, v54
	v_fmac_f32_e32 v7, v119, v54
	v_fmac_f32_e32 v8, v118, v54
	v_fmac_f32_e32 v9, v117, v54
	v_fmac_f32_e32 v10, v116, v54
	v_fmac_f32_e32 v11, v115, v54
	v_fmac_f32_e32 v12, v114, v54
	v_fmac_f32_e32 v13, v113, v54
	v_fmac_f32_e32 v14, v112, v54
	v_fmac_f32_e32 v15, v111, v54
	v_fmac_f32_e32 v1, v126, v55
	v_fmac_f32_e32 v2, v125, v55
	v_fmac_f32_e32 v3, v124, v55
	v_fmac_f32_e32 v4, v123, v55
	v_fmac_f32_e32 v5, v122, v55
	v_fmac_f32_e32 v6, v121, v55
	v_fmac_f32_e32 v7, v120, v55
	v_fmac_f32_e32 v8, v119, v55
	v_fmac_f32_e32 v9, v118, v55
	v_fmac_f32_e32 v10, v117, v55
	v_fmac_f32_e32 v11, v116, v55
	v_fmac_f32_e32 v12, v115, v55
	v_fmac_f32_e32 v13, v114, v55
	v_fmac_f32_e32 v14, v113, v55
	v_fmac_f32_e32 v15, v112, v55
	s_waitcnt lgkmcnt(6)
	v_fmac_f32_e32 v2, v126, v56
	v_fmac_f32_e32 v3, v125, v56
	v_fmac_f32_e32 v4, v124, v56
	v_fmac_f32_e32 v5, v123, v56
	v_fmac_f32_e32 v6, v122, v56
	v_fmac_f32_e32 v7, v121, v56
	v_fmac_f32_e32 v8, v120, v56
	v_fmac_f32_e32 v9, v119, v56
	v_fmac_f32_e32 v10, v118, v56
	v_fmac_f32_e32 v11, v117, v56
	v_fmac_f32_e32 v12, v116, v56
	v_fmac_f32_e32 v13, v115, v56
	v_fmac_f32_e32 v14, v114, v56
	v_fmac_f32_e32 v15, v113, v56
	v_fmac_f32_e32 v3, v126, v57
	v_fmac_f32_e32 v4, v125, v57
	v_fmac_f32_e32 v5, v124, v57
	v_fmac_f32_e32 v6, v123, v57
	v_fmac_f32_e32 v7, v122, v57
	v_fmac_f32_e32 v8, v121, v57
	v_fmac_f32_e32 v9, v120, v57
	v_fmac_f32_e32 v10, v119, v57
	v_fmac_f32_e32 v11, v118, v57
	v_fmac_f32_e32 v12, v117, v57
	v_fmac_f32_e32 v13, v116, v57
	v_fmac_f32_e32 v14, v115, v57
	v_fmac_f32_e32 v15, v114, v57
	s_waitcnt lgkmcnt(5)
	v_fmac_f32_e32 v4, v126, v58
	v_fmac_f32_e32 v5, v125, v58
	v_fmac_f32_e32 v6, v124, v58
	v_fmac_f32_e32 v7, v123, v58
	v_fmac_f32_e32 v8, v122, v58
	v_fmac_f32_e32 v9, v121, v58
	v_fmac_f32_e32 v10, v120, v58
	v_fmac_f32_e32 v11, v119, v58
	v_fmac_f32_e32 v12, v118, v58
	v_fmac_f32_e32 v13, v117, v58
	v_fmac_f32_e32 v14, v116, v58
	v_fmac_f32_e32 v15, v115, v58
	v_fmac_f32_e32 v5, v126, v59
	v_fmac_f32_e32 v6, v125, v59
	v_fmac_f32_e32 v7, v124, v59
	v_fmac_f32_e32 v8, v123, v59
	v_fmac_f32_e32 v9, v122, v59
	v_fmac_f32_e32 v10, v121, v59
	v_fmac_f32_e32 v11, v120, v59
	v_fmac_f32_e32 v12, v119, v59
	v_fmac_f32_e32 v13, v118, v59
	v_fmac_f32_e32 v14, v117, v59
	v_fmac_f32_e32 v15, v116, v59
	s_waitcnt lgkmcnt(4)
	v_fmac_f32_e32 v6, v126, v60
	v_fmac_f32_e32 v7, v125, v60
	v_fmac_f32_e32 v8, v124, v60
	v_fmac_f32_e32 v9, v123, v60
	v_fmac_f32_e32 v10, v122, v60
	v_fmac_f32_e32 v11, v121, v60
	v_fmac_f32_e32 v12, v120, v60
	v_fmac_f32_e32 v13, v119, v60
	v_fmac_f32_e32 v14, v118, v60
	v_fmac_f32_e32 v15, v117, v60
	v_fmac_f32_e32 v7, v126, v61
	v_fmac_f32_e32 v8, v125, v61
	v_fmac_f32_e32 v9, v124, v61
	v_fmac_f32_e32 v10, v123, v61
	v_fmac_f32_e32 v11, v122, v61
	v_fmac_f32_e32 v12, v121, v61
	v_fmac_f32_e32 v13, v120, v61
	v_fmac_f32_e32 v14, v119, v61
	v_fmac_f32_e32 v15, v118, v61
	s_waitcnt lgkmcnt(3)
	v_fmac_f32_e32 v8, v126, v62
	v_fmac_f32_e32 v9, v125, v62
	v_fmac_f32_e32 v10, v124, v62
	v_fmac_f32_e32 v11, v123, v62
	v_fmac_f32_e32 v12, v122, v62
	v_fmac_f32_e32 v13, v121, v62
	v_fmac_f32_e32 v14, v120, v62
	v_fmac_f32_e32 v15, v119, v62
	v_fmac_f32_e32 v9, v126, v63
	v_fmac_f32_e32 v10, v125, v63
	v_fmac_f32_e32 v11, v124, v63
	v_fmac_f32_e32 v12, v123, v63
	v_fmac_f32_e32 v13, v122, v63
	v_fmac_f32_e32 v14, v121, v63
	v_fmac_f32_e32 v15, v120, v63
	s_waitcnt lgkmcnt(2)
	v_fmac_f32_e32 v10, v126, v64
	v_fmac_f32_e32 v11, v125, v64
	v_fmac_f32_e32 v12, v124, v64
	v_fmac_f32_e32 v13, v123, v64
	v_fmac_f32_e32 v14, v122, v64
	v_fmac_f32_e32 v15, v121, v64
	v_fmac_f32_e32 v11, v126, v65
	v_fmac_f32_e32 v12, v125, v65
	v_fmac_f32_e32 v13, v124, v65
	v_fmac_f32_e32 v14, v123, v65
	v_fmac_f32_e32 v15, v122, v65
	s_waitcnt lgkmcnt(1)
	v_fmac_f32_e32 v12, v126, v66
	v_fmac_f32_e32 v13, v125, v66
	v_fmac_f32_e32 v14, v124, v66
	v_fmac_f32_e32 v15, v123, v66
	v_fmac_f32_e32 v13, v126, v67
	v_fmac_f32_e32 v14, v125, v67
	v_fmac_f32_e32 v15, v124, v67
	s_waitcnt lgkmcnt(0)
	v_fmac_f32_e32 v14, v126, v68
	v_fmac_f32_e32 v15, v125, v68
	v_fmac_f32_e32 v15, v126, v69
	ds_write2st64_b32 v238, v0, v1 offset0:0 offset1:4
	ds_write2st64_b32 v238, v2, v3 offset0:8 offset1:12
	ds_write2st64_b32 v238, v4, v5 offset0:16 offset1:20
	ds_write2st64_b32 v238, v6, v7 offset0:24 offset1:28
	ds_write2st64_b32 v238, v8, v9 offset0:32 offset1:36
	ds_write2st64_b32 v238, v10, v11 offset0:40 offset1:44
	ds_write2st64_b32 v238, v12, v13 offset0:48 offset1:52
	ds_write2st64_b32 v238, v14, v15 offset0:56 offset1:60
	s_waitcnt lgkmcnt(0)
	s_barrier
	ds_read_b128 v[0:3], v239 offset:0
	ds_read_b128 v[4:7], v239 offset:1024
	ds_read_b128 v[8:11], v239 offset:2048
	ds_read_b128 v[12:15], v239 offset:3072
	s_waitcnt lgkmcnt(0)
	v_add_f32_e32 v16, v0, v1
	v_add_f32_e32 v17, v4, v5
	v_add_f32_e32 v18, v8, v9
	v_add_f32_e32 v19, v12, v13
	v_add_f32_e32 v20, v2, v3
	v_add_f32_e32 v21, v6, v7
	v_add_f32_e32 v22, v10, v11
	v_add_f32_e32 v23, v14, v15
	v_add_f32_e32 v16, v16, v20
	v_add_f32_e32 v17, v17, v21
	v_add_f32_e32 v18, v18, v22
	v_add_f32_e32 v19, v19, v23
	v_add_f32_dpp v16, v16, v16 quad_perm:[1,0,3,2] row_mask:0xf bank_mask:0xf
	v_add_f32_dpp v17, v17, v17 quad_perm:[1,0,3,2] row_mask:0xf bank_mask:0xf
	v_add_f32_dpp v18, v18, v18 quad_perm:[1,0,3,2] row_mask:0xf bank_mask:0xf
	v_add_f32_dpp v19, v19, v19 quad_perm:[1,0,3,2] row_mask:0xf bank_mask:0xf
	v_add_f32_dpp v16, v16, v16 quad_perm:[2,3,0,1] row_mask:0xf bank_mask:0xf
	v_add_f32_dpp v17, v17, v17 quad_perm:[2,3,0,1] row_mask:0xf bank_mask:0xf
	v_add_f32_dpp v18, v18, v18 quad_perm:[2,3,0,1] row_mask:0xf bank_mask:0xf
	v_add_f32_dpp v19, v19, v19 quad_perm:[2,3,0,1] row_mask:0xf bank_mask:0xf
	v_add_f32_dpp v16, v16, v16 row_half_mirror row_mask:0xf bank_mask:0xf
	v_add_f32_dpp v17, v17, v17 row_half_mirror row_mask:0xf bank_mask:0xf
	v_add_f32_dpp v18, v18, v18 row_half_mirror row_mask:0xf bank_mask:0xf
	v_add_f32_dpp v19, v19, v19 row_half_mirror row_mask:0xf bank_mask:0xf
	v_add_f32_dpp v16, v16, v16 row_mirror row_mask:0xf bank_mask:0xf
	v_add_f32_dpp v17, v17, v17 row_mirror row_mask:0xf bank_mask:0xf
	v_add_f32_dpp v18, v18, v18 row_mirror row_mask:0xf bank_mask:0xf
	v_add_f32_dpp v19, v19, v19 row_mirror row_mask:0xf bank_mask:0xf
	v_mov_b32_e32 v20, v16
	v_mov_b32_e32 v21, v17
	v_mov_b32_e32 v22, v18
	v_mov_b32_e32 v23, v19
	v_permlane16_swap_b32_e32 v16, v20
	v_permlane16_swap_b32_e32 v17, v21
	v_permlane16_swap_b32_e32 v18, v22
	v_permlane16_swap_b32_e32 v19, v23
	v_add_f32_e32 v16, v16, v20
	v_add_f32_e32 v17, v17, v21
	v_add_f32_e32 v18, v18, v22
	v_add_f32_e32 v19, v19, v23
	v_mov_b32_e32 v20, v16
	v_mov_b32_e32 v21, v17
	v_mov_b32_e32 v22, v18
	v_mov_b32_e32 v23, v19
	v_permlane32_swap_b32_e32 v16, v20
	v_permlane32_swap_b32_e32 v17, v21
	v_permlane32_swap_b32_e32 v18, v22
	v_permlane32_swap_b32_e32 v19, v23
	v_add_f32_e32 v16, v16, v20
	v_add_f32_e32 v17, v17, v21
	v_add_f32_e32 v18, v18, v22
	v_add_f32_e32 v19, v19, v23
	v_mul_f32_e32 v16, 0x3b800000, v16
	v_mul_f32_e32 v17, 0x3b800000, v17
	v_mul_f32_e32 v18, 0x3b800000, v18
	v_mul_f32_e32 v19, 0x3b800000, v19
	v_sub_f32_e32 v0, v0, v16
	v_sub_f32_e32 v4, v4, v17
	v_sub_f32_e32 v8, v8, v18
	v_sub_f32_e32 v12, v12, v19
	v_sub_f32_e32 v1, v1, v16
	v_sub_f32_e32 v5, v5, v17
	v_sub_f32_e32 v9, v9, v18
	v_sub_f32_e32 v13, v13, v19
	v_sub_f32_e32 v2, v2, v16
	v_sub_f32_e32 v6, v6, v17
	v_sub_f32_e32 v10, v10, v18
	v_sub_f32_e32 v14, v14, v19
	v_sub_f32_e32 v3, v3, v16
	v_sub_f32_e32 v7, v7, v17
	v_sub_f32_e32 v11, v11, v18
	v_sub_f32_e32 v15, v15, v19
	v_mul_f32_e32 v20, v0, v0
	v_mul_f32_e32 v21, v4, v4
	v_mul_f32_e32 v22, v8, v8
	v_mul_f32_e32 v23, v12, v12
	v_fmac_f32_e32 v20, v1, v1
	v_fmac_f32_e32 v21, v5, v5
	v_fmac_f32_e32 v22, v9, v9
	v_fmac_f32_e32 v23, v13, v13
	v_fmac_f32_e32 v20, v2, v2
	v_fmac_f32_e32 v21, v6, v6
	v_fmac_f32_e32 v22, v10, v10
	v_fmac_f32_e32 v23, v14, v14
	v_fmac_f32_e32 v20, v3, v3
	v_fmac_f32_e32 v21, v7, v7
	v_fmac_f32_e32 v22, v11, v11
	v_fmac_f32_e32 v23, v15, v15
	v_add_f32_dpp v20, v20, v20 quad_perm:[1,0,3,2] row_mask:0xf bank_mask:0xf
	v_add_f32_dpp v21, v21, v21 quad_perm:[1,0,3,2] row_mask:0xf bank_mask:0xf
	v_add_f32_dpp v22, v22, v22 quad_perm:[1,0,3,2] row_mask:0xf bank_mask:0xf
	v_add_f32_dpp v23, v23, v23 quad_perm:[1,0,3,2] row_mask:0xf bank_mask:0xf
	v_add_f32_dpp v20, v20, v20 quad_perm:[2,3,0,1] row_mask:0xf bank_mask:0xf
	v_add_f32_dpp v21, v21, v21 quad_perm:[2,3,0,1] row_mask:0xf bank_mask:0xf
	v_add_f32_dpp v22, v22, v22 quad_perm:[2,3,0,1] row_mask:0xf bank_mask:0xf
	v_add_f32_dpp v23, v23, v23 quad_perm:[2,3,0,1] row_mask:0xf bank_mask:0xf
	v_add_f32_dpp v20, v20, v20 row_half_mirror row_mask:0xf bank_mask:0xf
	v_add_f32_dpp v21, v21, v21 row_half_mirror row_mask:0xf bank_mask:0xf
	v_add_f32_dpp v22, v22, v22 row_half_mirror row_mask:0xf bank_mask:0xf
	v_add_f32_dpp v23, v23, v23 row_half_mirror row_mask:0xf bank_mask:0xf
	v_add_f32_dpp v20, v20, v20 row_mirror row_mask:0xf bank_mask:0xf
	v_add_f32_dpp v21, v21, v21 row_mirror row_mask:0xf bank_mask:0xf
	v_add_f32_dpp v22, v22, v22 row_mirror row_mask:0xf bank_mask:0xf
	v_add_f32_dpp v23, v23, v23 row_mirror row_mask:0xf bank_mask:0xf
	v_mov_b32_e32 v16, v20
	v_mov_b32_e32 v17, v21
	v_mov_b32_e32 v18, v22
	v_mov_b32_e32 v19, v23
	v_permlane16_swap_b32_e32 v20, v16
	v_permlane16_swap_b32_e32 v21, v17
	v_permlane16_swap_b32_e32 v22, v18
	v_permlane16_swap_b32_e32 v23, v19
	v_add_f32_e32 v20, v20, v16
	v_add_f32_e32 v21, v21, v17
	v_add_f32_e32 v22, v22, v18
	v_add_f32_e32 v23, v23, v19
	v_mov_b32_e32 v16, v20
	v_mov_b32_e32 v17, v21
	v_mov_b32_e32 v18, v22
	v_mov_b32_e32 v19, v23
	v_permlane32_swap_b32_e32 v20, v16
	v_permlane32_swap_b32_e32 v21, v17
	v_permlane32_swap_b32_e32 v22, v18
	v_permlane32_swap_b32_e32 v23, v19
	v_add_f32_e32 v20, v20, v16
	v_add_f32_e32 v21, v21, v17
	v_add_f32_e32 v22, v22, v18
	v_add_f32_e32 v23, v23, v19
	v_mul_f32_e32 v20, 0x3b800000, v20
	v_mul_f32_e32 v21, 0x3b800000, v21
	v_mul_f32_e32 v22, 0x3b800000, v22
	v_mul_f32_e32 v23, 0x3b800000, v23
	v_add_f32_e32 v20, 0x358637bd, v20
	v_add_f32_e32 v21, 0x358637bd, v21
	v_add_f32_e32 v22, 0x358637bd, v22
	v_add_f32_e32 v23, 0x358637bd, v23
	v_rsq_f32_e32 v20, v20
	v_rsq_f32_e32 v21, v21
	v_rsq_f32_e32 v22, v22
	v_rsq_f32_e32 v23, v23
	v_mul_f32_e32 v0, v0, v20
	v_mul_f32_e32 v4, v4, v21
	v_mul_f32_e32 v8, v8, v22
	v_mul_f32_e32 v12, v12, v23
	v_mul_f32_e32 v1, v1, v20
	v_mul_f32_e32 v5, v5, v21
	v_mul_f32_e32 v9, v9, v22
	v_mul_f32_e32 v13, v13, v23
	v_mul_f32_e32 v2, v2, v20
	v_mul_f32_e32 v6, v6, v21
	v_mul_f32_e32 v10, v10, v22
	v_mul_f32_e32 v14, v14, v23
	v_mul_f32_e32 v3, v3, v20
	v_mul_f32_e32 v7, v7, v21
	v_mul_f32_e32 v11, v11, v22
	v_mul_f32_e32 v15, v15, v23
	v_fma_f32 v0, v0, v220, v224
	v_fma_f32 v4, v4, v220, v224
	v_fma_f32 v8, v8, v220, v224
	v_fma_f32 v12, v12, v220, v224
	v_fma_f32 v1, v1, v221, v225
	v_fma_f32 v5, v5, v221, v225
	v_fma_f32 v9, v9, v221, v225
	v_fma_f32 v13, v13, v221, v225
	v_fma_f32 v2, v2, v222, v226
	v_fma_f32 v6, v6, v222, v226
	v_fma_f32 v10, v10, v222, v226
	v_fma_f32 v14, v14, v222, v226
	v_fma_f32 v3, v3, v223, v227
	v_fma_f32 v7, v7, v223, v227
	v_fma_f32 v11, v11, v223, v227
	v_fma_f32 v15, v15, v223, v227
	v_mul_f32_e32 v48, 0xbfb8aa3b, v0
	v_mul_f32_e32 v52, 0xbfb8aa3b, v4
	v_mul_f32_e32 v56, 0xbfb8aa3b, v8
	v_mul_f32_e32 v60, 0xbfb8aa3b, v12
	v_mul_f32_e32 v49, 0xbfb8aa3b, v1
	v_mul_f32_e32 v53, 0xbfb8aa3b, v5
	v_mul_f32_e32 v57, 0xbfb8aa3b, v9
	v_mul_f32_e32 v61, 0xbfb8aa3b, v13
	v_mul_f32_e32 v50, 0xbfb8aa3b, v2
	v_mul_f32_e32 v54, 0xbfb8aa3b, v6
	v_mul_f32_e32 v58, 0xbfb8aa3b, v10
	v_mul_f32_e32 v62, 0xbfb8aa3b, v14
	v_mul_f32_e32 v51, 0xbfb8aa3b, v3
	v_mul_f32_e32 v55, 0xbfb8aa3b, v7
	v_mul_f32_e32 v59, 0xbfb8aa3b, v11
	v_mul_f32_e32 v63, 0xbfb8aa3b, v15
	v_exp_f32_e32 v48, v48
	v_exp_f32_e32 v52, v52
	v_exp_f32_e32 v56, v56
	v_exp_f32_e32 v60, v60
	v_exp_f32_e32 v49, v49
	v_exp_f32_e32 v53, v53
	v_exp_f32_e32 v57, v57
	v_exp_f32_e32 v61, v61
	v_exp_f32_e32 v50, v50
	v_exp_f32_e32 v54, v54
	v_exp_f32_e32 v58, v58
	v_exp_f32_e32 v62, v62
	v_exp_f32_e32 v51, v51
	v_exp_f32_e32 v55, v55
	v_exp_f32_e32 v59, v59
	v_exp_f32_e32 v63, v63
	v_add_f32_e32 v48, 1.0, v48
	v_add_f32_e32 v52, 1.0, v52
	v_add_f32_e32 v56, 1.0, v56
	v_add_f32_e32 v60, 1.0, v60
	v_add_f32_e32 v49, 1.0, v49
	v_add_f32_e32 v53, 1.0, v53
	v_add_f32_e32 v57, 1.0, v57
	v_add_f32_e32 v61, 1.0, v61
	v_add_f32_e32 v50, 1.0, v50
	v_add_f32_e32 v54, 1.0, v54
	v_add_f32_e32 v58, 1.0, v58
	v_add_f32_e32 v62, 1.0, v62
	v_add_f32_e32 v51, 1.0, v51
	v_add_f32_e32 v55, 1.0, v55
	v_add_f32_e32 v59, 1.0, v59
	v_add_f32_e32 v63, 1.0, v63
	v_rcp_f32_e32 v48, v48
	v_rcp_f32_e32 v52, v52
	v_rcp_f32_e32 v56, v56
	v_rcp_f32_e32 v60, v60
	v_rcp_f32_e32 v49, v49
	v_rcp_f32_e32 v53, v53
	v_rcp_f32_e32 v57, v57
	v_rcp_f32_e32 v61, v61
	v_rcp_f32_e32 v50, v50
	v_rcp_f32_e32 v54, v54
	v_rcp_f32_e32 v58, v58
	v_rcp_f32_e32 v62, v62
	v_rcp_f32_e32 v51, v51
	v_rcp_f32_e32 v55, v55
	v_rcp_f32_e32 v59, v59
	v_rcp_f32_e32 v63, v63
	v_mul_f32_e32 v0, v0, v48
	v_mul_f32_e32 v4, v4, v52
	v_mul_f32_e32 v8, v8, v56
	v_mul_f32_e32 v12, v12, v60
	v_mul_f32_e32 v1, v1, v49
	v_mul_f32_e32 v5, v5, v53
	v_mul_f32_e32 v9, v9, v57
	v_mul_f32_e32 v13, v13, v61
	v_mul_f32_e32 v2, v2, v50
	v_mul_f32_e32 v6, v6, v54
	v_mul_f32_e32 v10, v10, v58
	v_mul_f32_e32 v14, v14, v62
	v_mul_f32_e32 v3, v3, v51
	v_mul_f32_e32 v7, v7, v55
	v_mul_f32_e32 v11, v11, v59
	v_mul_f32_e32 v15, v15, v63
	v_cvt_pk_bf16_f32 v64, v0, v1
	v_cvt_pk_bf16_f32 v65, v2, v3
	v_cvt_pk_bf16_f32 v66, v4, v5
	v_cvt_pk_bf16_f32 v67, v6, v7
	v_cvt_pk_bf16_f32 v68, v8, v9
	v_cvt_pk_bf16_f32 v69, v10, v11
	v_cvt_pk_bf16_f32 v70, v12, v13
	v_cvt_pk_bf16_f32 v71, v14, v15
	global_store_dwordx2 v240, v[64:65], s[8:9] offset:0
	global_store_dwordx2 v240, v[66:67], s[8:9] offset:512
	global_store_dwordx2 v240, v[68:69], s[8:9] offset:1024
	global_store_dwordx2 v240, v[70:71], s[8:9] offset:1536
	s_add_u32 s13, s4, 0x100
	s_cmp_ge_u32 s13, 0x400
	s_cselect_b32 s13, s26, s13
	s_cmp_ge_u32 s4, 0x400
	s_cselect_b32 s4, 0x7fff, s13
	s_cmp_lt_u32 s4, s5
	s_cbranch_scc1 .Lcv_loop
	s_waitcnt vmcnt(0)
